# attention softmax row-sum: the 16 dependent packed f32 adds per k-tile replaced by 32 scalar adds (two independent chains), bit-identical
# speedup vs baseline: 1.0038x; 1.0038x over previous
; #define MFMA16(a, b, c) __builtin_amdgcn_mfma_f32_16x16x32_bf16((a), (b), (c), 0, 0, 0)
; DI unsigned pk2(float lo, float hi) { f32x2 v = {lo, hi}; return __builtin_bit_cast(unsigned, __builtin_convertvector(v, bf16x2_t)); }
; DI float fexp2(float x) { return __builtin_amdgcn_exp2f(x); }
;     ...
;                 float ps = 0.f;
; #pragma unroll
;                 for (int kb = 0; kb < 4; ++kb)
; #pragma unroll
;                     for (int rr = 0; rr < 4; ++rr) { const float pv = fexp2(as[kb][qb][rr] - mnew); as[kb][qb][rr] = pv; ps += pv; }
;                 lsum[qb] = lsum[qb] * alpha[qb] + ps;
;             }
;             if (__builtin_amdgcn_ballot_w64(alpha[0] != 1.f || alpha[1] != 1.f) != 0ull) {
; #pragma unroll
;                 for (int d = 0; d < 8; ++d)
; #pragma unroll
;                     for (int qb = 0; qb < 2; ++qb) ao[d][qb] = ao[d][qb] * alpha[qb];
;             }
;             bf16x8 pf[2][2];
; #pragma unroll
;             for (int k2 = 0; k2 < 2; ++k2)
; #pragma unroll
;                 for (int qb = 0; qb < 2; ++qb) {
;                     u32x4 pkd;
;                     pkd.x = pk2(as[2 * k2][qb][0], as[2 * k2][qb][1]); pkd.y = pk2(as[2 * k2][qb][2], as[2 * k2][qb][3]);
;                     pkd.z = pk2(as[2 * k2 + 1][qb][0], as[2 * k2 + 1][qb][1]); pkd.w = pk2(as[2 * k2 + 1][qb][2], as[2 * k2 + 1][qb][3]);
;                     pf[k2][qb] = __builtin_bit_cast(bf16x8, pkd);
;                 }
; #pragma unroll
;             for (int k2 = 0; k2 < 2; ++k2) {
;                 const int ph = ((4 * k2 + qq) ^ vkey) << 4;
; #pragma unroll
;                 for (int d = 0; d < 8; ++d) {
;                     const bf16x8 vf = *(const bf16x8*)(sb + AT_KB + (d * 16 + r16) * 128 + ph);
; #pragma unroll
;                     for (int qb = 0; qb < 2; ++qb) ao[d][qb] = MFMA16(vf, pf[k2][qb], ao[d][qb]);
;                 }
;             }
.LBB0_938:
	v_sub_f32_e32 v129, v129, v146
	v_exp_f32_e32 v148, v129
	v_sub_f32_e32 v129, v130, v146
	v_sub_f32_e32 v128, v128, v146
	v_exp_f32_e32 v130, v129
	v_sub_f32_e32 v129, v131, v146
	v_sub_f32_e32 v124, v124, v146
	v_sub_f32_e32 v116, v116, v147
	v_sub_f32_e32 v112, v112, v147
	v_exp_f32_e32 v128, v128
	v_exp_f32_e32 v150, v129
	v_exp_f32_e32 v152, v124
	v_sub_f32_e32 v124, v125, v146
	v_exp_f32_e32 v129, v116
	v_sub_f32_e32 v116, v117, v147
	v_exp_f32_e32 v153, v112
	v_sub_f32_e32 v112, v113, v147
	v_exp_f32_e32 v154, v124
	v_sub_f32_e32 v124, v126, v146
	v_exp_f32_e32 v149, v116
	v_sub_f32_e32 v116, v118, v147
	v_exp_f32_e32 v155, v112
	v_sub_f32_e32 v112, v114, v147
	v_exp_f32_e32 v126, v124
	v_sub_f32_e32 v124, v127, v146
	v_exp_f32_e32 v131, v116
	v_sub_f32_e32 v116, v119, v147
	v_exp_f32_e32 v127, v112
	v_sub_f32_e32 v112, v115, v147
	v_exp_f32_e32 v156, v124
	v_sub_f32_e32 v124, v132, v146
	v_exp_f32_e32 v151, v116
	v_exp_f32_e32 v157, v112
	v_sub_f32_e32 v112, v120, v147
	v_exp_f32_e32 v132, v124
	v_sub_f32_e32 v124, v133, v146
	v_exp_f32_e32 v133, v112
	v_add_f32_e32 v112, 0, v128
	v_add_f32_e32 v113, 0, v129
	v_sub_f32_e32 v114, v121, v147
	v_add_f32_e32 v112, v148, v112
	v_add_f32_e32 v113, v149, v113
	v_exp_f32_e32 v158, v124
	v_add_f32_e32 v112, v130, v112
	v_add_f32_e32 v113, v131, v113
	v_sub_f32_e32 v124, v134, v146
	v_add_f32_e32 v112, v150, v112
	v_add_f32_e32 v113, v151, v113
	v_exp_f32_e32 v159, v114
	v_add_f32_e32 v112, v152, v112
	v_add_f32_e32 v113, v153, v113
	v_sub_f32_e32 v114, v122, v147
	v_add_f32_e32 v112, v154, v112
	v_add_f32_e32 v113, v155, v113
	v_exp_f32_e32 v134, v124
	v_sub_f32_e32 v124, v135, v146
	v_add_f32_e32 v112, v126, v112
	v_add_f32_e32 v113, v127, v113
	v_exp_f32_e32 v135, v114
	v_sub_f32_e32 v114, v123, v147
	v_exp_f32_e32 v208, v124
	v_sub_f32_e32 v124, v140, v146
	v_add_f32_e32 v112, v156, v112
	v_add_f32_e32 v113, v157, v113
	v_exp_f32_e32 v209, v114
	v_sub_f32_e32 v114, v136, v147
	v_exp_f32_e32 v140, v124
	v_sub_f32_e32 v124, v141, v146
	v_add_f32_e32 v112, v132, v112
	v_add_f32_e32 v113, v133, v113
	v_exp_f32_e32 v141, v114
	v_sub_f32_e32 v114, v137, v147
	v_exp_f32_e32 v214, v124
	v_sub_f32_e32 v124, v142, v146
	v_exp_f32_e32 v215, v114
	v_sub_f32_e32 v114, v138, v147
	v_add_f32_e32 v112, v158, v112
	v_add_f32_e32 v113, v159, v113
	v_exp_f32_e32 v142, v124
	v_sub_f32_e32 v124, v143, v146
	v_exp_f32_e32 v143, v114
	v_sub_f32_e32 v114, v139, v147
	v_add_f32_e32 v112, v134, v112
	v_add_f32_e32 v113, v135, v113
	v_exp_f32_e32 v220, v124
	v_exp_f32_e32 v221, v114
	v_add_f32_e32 v112, v208, v112
	v_add_f32_e32 v113, v209, v113
	v_cvt_pk_bf16_f32 v116, v132, v158
	v_add_f32_e32 v112, v140, v112
	v_add_f32_e32 v113, v141, v113
	v_add_f32_e32 v112, v214, v112
	v_add_f32_e32 v113, v215, v113
	v_cvt_pk_bf16_f32 v120, v128, v148
	v_add_f32_e32 v112, v142, v112
	v_add_f32_e32 v113, v143, v113
	v_cvt_pk_bf16_f32 v121, v130, v150
	v_add_f32_e32 v112, v220, v112
	v_add_f32_e32 v113, v221, v113
	v_cvt_pk_bf16_f32 v124, v129, v149
	v_pk_fma_f32 v[172:173], v[172:173], v[144:145], v[112:113]
	v_cvt_pk_bf16_f32 v112, v133, v159
	v_cvt_pk_bf16_f32 v125, v131, v151
	ds_read_b128 v[128:131], v248 offset:30720
	v_cvt_pk_bf16_f32 v122, v152, v154
	v_cvt_pk_bf16_f32 v123, v126, v156
	v_cvt_pk_bf16_f32 v126, v153, v155
	v_cvt_pk_bf16_f32 v127, v127, v157
	s_waitcnt lgkmcnt(3)
	v_mfma_f32_16x16x32_bf16 v[56:59], v[236:239], v[120:123], v[56:59]
	v_cvt_pk_bf16_f32 v117, v134, v208
	v_cvt_pk_bf16_f32 v118, v140, v214
	v_cvt_pk_bf16_f32 v119, v142, v220
	v_mfma_f32_16x16x32_bf16 v[44:47], v[236:239], v[124:127], v[44:47]
	ds_read_b128 v[236:239], v248 offset:32768
	v_cvt_pk_bf16_f32 v113, v135, v209
	v_cvt_pk_bf16_f32 v114, v141, v215
	s_waitcnt lgkmcnt(3)
	v_mfma_f32_16x16x32_bf16 v[60:63], v[240:243], v[120:123], v[60:63]
	v_cvt_pk_bf16_f32 v115, v143, v221
	v_mov_b32_e32 v224, v147
	v_mov_b32_e32 v225, v146
	v_mfma_f32_16x16x32_bf16 v[48:51], v[240:243], v[124:127], v[48:51]
	ds_read_b128 v[240:243], v248 offset:34816
	s_waitcnt lgkmcnt(3)
	v_mfma_f32_16x16x32_bf16 v[52:55], v[244:247], v[120:123], v[52:55]
	v_mfma_f32_16x16x32_bf16 v[36:39], v[244:247], v[124:127], v[36:39]
	ds_read_b128 v[244:247], v248 offset:36864
	s_waitcnt lgkmcnt(3)
	v_mfma_f32_16x16x32_bf16 v[40:43], v[128:131], v[120:123], v[40:43]
	v_mfma_f32_16x16x32_bf16 v[28:31], v[128:131], v[124:127], v[28:31]
	ds_read_b128 v[128:131], v248 offset:38912
	s_waitcnt lgkmcnt(3)
	v_mfma_f32_16x16x32_bf16 v[32:35], v[236:239], v[120:123], v[32:35]
	v_mfma_f32_16x16x32_bf16 v[16:19], v[236:239], v[124:127], v[16:19]
	ds_read_b128 v[236:239], v250 offset:24576
	s_waitcnt lgkmcnt(3)
	v_mfma_f32_16x16x32_bf16 v[20:23], v[240:243], v[120:123], v[20:23]
	v_mfma_f32_16x16x32_bf16 v[0:3], v[240:243], v[124:127], v[0:3]
	ds_read_b128 v[240:243], v250 offset:26624
	s_waitcnt lgkmcnt(3)
	v_mfma_f32_16x16x32_bf16 v[8:11], v[244:247], v[120:123], v[8:11]
	v_mfma_f32_16x16x32_bf16 v[4:7], v[244:247], v[124:127], v[4:7]
	ds_read_b128 v[244:247], v250 offset:28672
	s_waitcnt lgkmcnt(3)
	v_mfma_f32_16x16x32_bf16 v[24:27], v[128:131], v[120:123], v[24:27]
	v_mfma_f32_16x16x32_bf16 v[12:15], v[128:131], v[124:127], v[12:15]
	ds_read_b128 v[128:131], v250 offset:30720
	s_waitcnt lgkmcnt(3)
	v_mfma_f32_16x16x32_bf16 v[56:59], v[236:239], v[116:119], v[56:59]
	v_mfma_f32_16x16x32_bf16 v[44:47], v[236:239], v[112:115], v[44:47]
	ds_read_b128 v[236:239], v250 offset:32768
	s_waitcnt lgkmcnt(3)
	v_mfma_f32_16x16x32_bf16 v[60:63], v[240:243], v[116:119], v[60:63]
	v_mfma_f32_16x16x32_bf16 v[48:51], v[240:243], v[112:115], v[48:51]
	ds_read_b128 v[240:243], v250 offset:34816
	s_waitcnt lgkmcnt(3)
	v_mfma_f32_16x16x32_bf16 v[52:55], v[244:247], v[116:119], v[52:55]
	v_mfma_f32_16x16x32_bf16 v[36:39], v[244:247], v[112:115], v[36:39]
	ds_read_b128 v[244:247], v250 offset:36864
	s_waitcnt lgkmcnt(3)
	v_mfma_f32_16x16x32_bf16 v[40:43], v[128:131], v[116:119], v[40:43]
	v_mfma_f32_16x16x32_bf16 v[28:31], v[128:131], v[112:115], v[28:31]
	ds_read_b128 v[128:131], v250 offset:38912
	s_waitcnt lgkmcnt(3)
	v_mfma_f32_16x16x32_bf16 v[32:35], v[236:239], v[116:119], v[32:35]
	v_mfma_f32_16x16x32_bf16 v[16:19], v[236:239], v[112:115], v[16:19]
	s_waitcnt lgkmcnt(2)
	v_mfma_f32_16x16x32_bf16 v[20:23], v[240:243], v[116:119], v[20:23]
	v_mfma_f32_16x16x32_bf16 v[0:3], v[240:243], v[112:115], v[0:3]
	s_waitcnt lgkmcnt(1)
	v_mfma_f32_16x16x32_bf16 v[8:11], v[244:247], v[116:119], v[8:11]
	v_mfma_f32_16x16x32_bf16 v[4:7], v[244:247], v[112:115], v[4:7]
	s_waitcnt lgkmcnt(0)
	v_mfma_f32_16x16x32_bf16 v[24:27], v[128:131], v[116:119], v[24:27]
	v_mfma_f32_16x16x32_bf16 v[12:15], v[128:131], v[112:115], v[12:15]
